# A1: second-half stream also issues its K prefill reads before its softmax block; both streams do end-of-tile bookkeeping before the barrier
# baseline (speedup 1.0000x reference)
; DI unsigned cvtpk(float lo, float hi) { f32x2 v = {lo, hi}; return __builtin_bit_cast(unsigned, __builtin_convertvector(v, bf16x2_t)); }
; template <int NHQ, int NHKV>
; DI void attn_phase_l1(const u16* __restrict__ Q, const u16* __restrict__ K, const u16* __restrict__ Vt, u16* __restrict__ O, const float* __restrict__ qg, char* smem, const int wv) {
;     ...
;         for (int i = 0; i < NM; ++i) {
;           if (i < NQK) {
;             if (i & 1) s1 = __builtin_amdgcn_mfma_f32_32x32x16_bf16(ring[i % RING], qf[i >> 1], s1, 0, 0, 0);
;             else       s0 = __builtin_amdgcn_mfma_f32_32x32x16_bf16(ring[i % RING], qf[i >> 1], s0, 0, 0, 0);
;           } else {
;             o[(i - NQK) & 3] = __builtin_amdgcn_mfma_f32_32x32x16_bf16(ring[i % RING], pb[(i - NQK) >> 2], o[(i - NQK) & 3], 0, 0, 0);
;           }
;           if (i + RING < NM) B_FRAG(ring[i % RING], i + RING);
;           if (i >= NQK + 2) {
;             const int g = i - NQK - 2;
;             f32x2 v;
;             if (g < 8) { v[0] = __builtin_amdgcn_exp2f(s0[2 * g]); v[1] = __builtin_amdgcn_exp2f(s0[2 * g + 1]); }
;             else       { v[0] = __builtin_amdgcn_exp2f(s1[2 * (g - 8)]); v[1] = __builtin_amdgcn_exp2f(s1[2 * (g - 8) + 1]); }
;             ps2 += v; w_[g] = cvtpk(v[0], v[1]);
;           }
;           __builtin_amdgcn_sched_barrier(0);
;         }
; #pragma unroll
;         for (int g = 14; g < 16; ++g) { f32x2 v; v[0] = __builtin_amdgcn_exp2f(s1[2 * (g - 8)]); v[1] = __builtin_amdgcn_exp2f(s1[2 * (g - 8) + 1]); ps2 += v; w_[g] = cvtpk(v[0], v[1]); }
;     ...
;         if (j + 1 == NT - 1) {
;           ps2 = f32x2{0.f, 0.f};
; #pragma unroll
;           for (int g = 0; g < 4; ++g) { ps2[0] += __builtin_amdgcn_exp2f(s0[2 * g]); ps2[1] += __builtin_amdgcn_exp2f(s0[2 * g + 1]); }
; #pragma unroll
;           for (int g = 4; g < 16; ++g) w_[g] = 0u;
;         }
;         if (j + 1 < NT) {
;           l += ps2[0] + ps2[1];
; #pragma unroll
;           for (int q = 0; q < 4; ++q) pb[q] = __builtin_bit_cast(bf16x8, u32x4{w_[4 * q], w_[4 * q + 1], w_[4 * q + 2], w_[4 * q + 3]});
;         }
;       }
;       asm volatile("s_waitcnt lgkmcnt(0)" ::: "memory"); __builtin_amdgcn_s_barrier(); asm volatile("" ::: "memory");
.Lmy_a1_skipk:
	v_mfma_f32_32x32x16_bf16 v[64:79], v[214:217], v[104:107], v[64:79]
	v_lshl_add_u64 v[240:241], s[6:7], 0, v[174:175]
	v_add_co_u32_e32 v244, vcc, 0x29900000, v240
	s_nop 1
	v_addc_co_u32_e32 v245, vcc, 0, v241, vcc
	v_add_co_u32_e32 v240, vcc, 0x29982000, v240
	s_nop 1
	v_addc_co_u32_e32 v241, vcc, 0, v241, vcc
	global_load_dwordx4 v[136:139], v[244:245], off offset:256
	global_load_dwordx4 v[140:143], v[240:241], off offset:256
	s_waitcnt lgkmcnt(11)
	v_mfma_f32_32x32x16_bf16 v[80:95], v[220:223], v[116:119], v[80:95]
	ds_read_b128 v[214:217], v177 offset:34816
	ds_read_b128 v[220:223], v177 offset:39424
	s_waitcnt lgkmcnt(11)
	v_mfma_f32_32x32x16_bf16 v[64:79], v[224:227], v[116:119], v[64:79]
	v_mfma_f32_32x32x16_bf16 v[80:95], v[228:231], v[120:123], v[80:95]
	ds_read_b128 v[224:227], v177 offset:44032
	ds_read_b128 v[228:231], v177 offset:48640
	s_waitcnt lgkmcnt(9)
	v_mfma_f32_32x32x16_bf16 v[64:79], v[178:181], v[120:123], v[64:79]
	v_mfma_f32_32x32x16_bf16 v[80:95], v[182:185], v[112:115], v[80:95]
	ds_read_b128 v[178:181], v177 offset:34848
	ds_read_b128 v[182:185], v177 offset:39456
	s_waitcnt lgkmcnt(7)
	v_mfma_f32_32x32x16_bf16 v[64:79], v[190:193], v[112:115], v[64:79]
	v_mfma_f32_32x32x16_bf16 v[80:95], v[186:189], v[124:127], v[80:95]
	ds_read_b128 v[190:193], v177 offset:44064
	ds_read_b128 v[186:189], v177 offset:48672
	s_waitcnt lgkmcnt(7)
	v_mfma_f32_32x32x16_bf16 v[64:79], v[194:197], v[124:127], v[64:79]
	v_mfma_f32_32x32x16_bf16 v[48:63], v[214:217], v[144:147], v[48:63]
	ds_read_b128 v[194:197], v177 offset:34880
	s_waitcnt lgkmcnt(7)
	v_mfma_f32_32x32x16_bf16 v[32:47], v[220:223], v[144:147], v[32:47]
	ds_read_b128 v[214:217], v177 offset:39488
	s_waitcnt lgkmcnt(7)
	v_mfma_f32_32x32x16_bf16 v[16:31], v[224:227], v[144:147], v[16:31]
	s_nop 0
	v_exp_f32_e32 v80, v80
	v_exp_f32_e32 v81, v81
	ds_read_b128 v[220:223], v177 offset:44096
	v_mov_b32_e32 v198, v80
	v_mov_b32_e32 v199, v81
	v_cvt_pk_bf16_f32 v80, v80, v81
	s_waitcnt lgkmcnt(7)
	v_mfma_f32_32x32x16_bf16 v[0:15], v[228:231], v[144:147], v[0:15]
	v_exp_f32_e32 v82, v82
	v_exp_f32_e32 v83, v83
	ds_read_b128 v[224:227], v177 offset:48704
	v_cvt_pk_bf16_f32 v145, v82, v83
	v_add_f32_e32 v198, v82, v198
	v_add_f32_e32 v199, v83, v199
	s_waitcnt lgkmcnt(7)
	v_mfma_f32_32x32x16_bf16 v[48:63], v[178:181], v[148:151], v[48:63]
	v_exp_f32_e32 v82, v84
	v_exp_f32_e32 v83, v85
	ds_read_b128 v[228:231], v177 offset:34912
	v_add_f32_e32 v84, v82, v198
	v_add_f32_e32 v85, v83, v199
	v_cvt_pk_bf16_f32 v146, v82, v83
	s_waitcnt lgkmcnt(7)
	v_mfma_f32_32x32x16_bf16 v[32:47], v[182:185], v[148:151], v[32:47]
	v_exp_f32_e32 v82, v86
	v_exp_f32_e32 v83, v87
	ds_read_b128 v[178:181], v177 offset:39520
	v_add_f32_e32 v84, v82, v84
	v_add_f32_e32 v85, v83, v85
	v_cvt_pk_bf16_f32 v147, v82, v83
	s_waitcnt lgkmcnt(7)
	v_mfma_f32_32x32x16_bf16 v[16:31], v[190:193], v[148:151], v[16:31]
	v_exp_f32_e32 v82, v88
	v_exp_f32_e32 v83, v89
	ds_read_b128 v[182:185], v177 offset:44128
	v_add_f32_e32 v86, v82, v84
	v_add_f32_e32 v87, v83, v85
	v_cvt_pk_bf16_f32 v84, v82, v83
	s_waitcnt lgkmcnt(7)
	v_mfma_f32_32x32x16_bf16 v[0:15], v[186:189], v[148:151], v[0:15]
	v_exp_f32_e32 v82, v90
	v_exp_f32_e32 v83, v91
	ds_read_b128 v[190:193], v177 offset:48736
	v_cvt_pk_bf16_f32 v149, v82, v83
	v_add_f32_e32 v86, v82, v86
	v_add_f32_e32 v87, v83, v87
	s_waitcnt lgkmcnt(7)
	v_mfma_f32_32x32x16_bf16 v[48:63], v[194:197], v[152:155], v[48:63]
	v_exp_f32_e32 v82, v92
	v_exp_f32_e32 v83, v93
	s_nop 0
	v_cvt_pk_bf16_f32 v150, v82, v83
	v_add_f32_e32 v86, v82, v86
	v_add_f32_e32 v87, v83, v87
	s_waitcnt lgkmcnt(6)
	v_mfma_f32_32x32x16_bf16 v[32:47], v[214:217], v[152:155], v[32:47]
	v_exp_f32_e32 v82, v94
	v_exp_f32_e32 v83, v95
	s_nop 0
	v_cvt_pk_bf16_f32 v151, v82, v83
	v_add_f32_e32 v86, v82, v86
	v_add_f32_e32 v87, v83, v87
	s_waitcnt lgkmcnt(5)
	v_mfma_f32_32x32x16_bf16 v[16:31], v[220:223], v[152:155], v[16:31]
	v_exp_f32_e32 v64, v64
	v_exp_f32_e32 v65, v65
	s_nop 0
	v_cvt_pk_bf16_f32 v88, v64, v65
	v_add_f32_e32 v82, v64, v86
	v_add_f32_e32 v83, v65, v87
	s_waitcnt lgkmcnt(4)
	v_mfma_f32_32x32x16_bf16 v[0:15], v[224:227], v[152:155], v[0:15]
	v_exp_f32_e32 v64, v66
	v_exp_f32_e32 v65, v67
	s_nop 0
	v_cvt_pk_bf16_f32 v153, v64, v65
	v_add_f32_e32 v66, v64, v82
	v_add_f32_e32 v67, v65, v83
	s_waitcnt lgkmcnt(3)
	v_mfma_f32_32x32x16_bf16 v[48:63], v[228:231], v[156:159], v[48:63]
	v_exp_f32_e32 v64, v68
	v_exp_f32_e32 v65, v69
	s_nop 0
	v_cvt_pk_bf16_f32 v154, v64, v65
	v_add_f32_e32 v66, v64, v66
	v_add_f32_e32 v67, v65, v67
	s_waitcnt lgkmcnt(2)
	v_mfma_f32_32x32x16_bf16 v[32:47], v[178:181], v[156:159], v[32:47]
	v_exp_f32_e32 v64, v70
	v_exp_f32_e32 v65, v71
	s_nop 0
	v_cvt_pk_bf16_f32 v155, v64, v65
	v_add_f32_e32 v66, v64, v66
	v_add_f32_e32 v67, v65, v67
	s_waitcnt lgkmcnt(1)
	v_mfma_f32_32x32x16_bf16 v[16:31], v[182:185], v[156:159], v[16:31]
	v_exp_f32_e32 v64, v72
	v_exp_f32_e32 v65, v73
	s_nop 0
	v_cvt_pk_bf16_f32 v92, v64, v65
	v_add_f32_e32 v66, v64, v66
	v_add_f32_e32 v67, v65, v67
	s_waitcnt lgkmcnt(0)
	v_mfma_f32_32x32x16_bf16 v[0:15], v[190:193], v[156:159], v[0:15]
	v_exp_f32_e32 v64, v74
	v_exp_f32_e32 v65, v75
	s_nop 0
	v_cvt_pk_bf16_f32 v157, v64, v65
	v_add_f32_e32 v64, v64, v66
	v_add_f32_e32 v65, v65, v67
	v_exp_f32_e32 v66, v76
	v_exp_f32_e32 v67, v77
	v_exp_f32_e32 v68, v78
	v_exp_f32_e32 v69, v79
	s_waitcnt lgkmcnt(0)
	v_add_f32_e32 v64, v66, v64
	v_add_f32_e32 v65, v67, v65
	v_add_f32_e32 v64, v68, v64
	v_add_f32_e32 v65, v69, v65
	s_add_u32 s24, s24, 0x8000
	v_add_f32_e32 v64, v64, v65
	s_addc_u32 s25, s25, 0
	v_cvt_pk_bf16_f32 v158, v66, v67
	v_cvt_pk_bf16_f32 v159, v68, v69
	v_add_f32_e32 v176, v176, v64
	s_cmp_eq_u32 s27, 62
	v_lshl_add_u64 v[174:175], v[174:175], 0, s[16:17]
	s_barrier
	s_cbranch_scc1 .LBB0_1215
	s_mov_b32 s42, s27
	s_branch .LBB0_1217
; template <int NHQ, int NHKV>
; DI void attn_phase_l1(const u16* __restrict__ Q, const u16* __restrict__ K, const u16* __restrict__ Vt, u16* __restrict__ O, const float* __restrict__ qg, char* smem, const int wv) {
;     ...
;     for (int j = 0; j < NT; ++j) {
;       if (j + 2 < NT) B_WRITEK(j & 1);
;       if (j + 1 < NT) B_WRITEV((j + 1) & 1);
;       __builtin_amdgcn_sched_barrier(0);
;       if (j + 3 < NT) B_LOADK(Kb, j + 3);
;       if (j + 2 < NT) B_LOADV(Vb, j + 2);
;       __builtin_amdgcn_sched_barrier(0);
;       if (j == NT - 1) {
;         const char* svl = vb0 + (j & 1) * VBYTES + r32 * VSTR + hh * 16;
;         bf16x8 vf[4];
; #pragma unroll
;         for (int d = 0; d < 4; ++d) vf[d] = *(const bf16x8*)(svl + d * 32 * VSTR);
; #pragma unroll
;         for (int d = 0; d < 4; ++d) o[d] = __builtin_amdgcn_mfma_f32_32x32x16_bf16(vf[d], pb[0], o[d], 0, 0, 0);
;       } else {
;         constexpr int NQK = 2 * NS, NM = NQK + 16, RING = 8;
;         const char* sk = kb0 + ((j + 1) & 1) * KBYTES + r32 * KSTR + hh * 16;
;         const char* sv = vb0 + (j & 1) * VBYTES + r32 * VSTR + hh * 16;
;         bf16x8 ring[RING];
;         unsigned w_[16]; f32x2 ps2 = {0.f, 0.f};
;     ...
; #pragma unroll
;         for (int i = 0; i < 16; ++i) { s0[i] = 0.f; s1[i] = 0.f; }
; #pragma unroll
;         for (int i = 0; i < RING; ++i) B_FRAG(ring[i], i);
; #pragma unroll
;         for (int i = 0; i < NM; ++i) {
;           if (i < NQK) {
;             if (i & 1) s1 = __builtin_amdgcn_mfma_f32_32x32x16_bf16(ring[i % RING], qf[i >> 1], s1, 0, 0, 0);
;             else       s0 = __builtin_amdgcn_mfma_f32_32x32x16_bf16(ring[i % RING], qf[i >> 1], s0, 0, 0, 0);
;           } else {
;             o[(i - NQK) & 3] = __builtin_amdgcn_mfma_f32_32x32x16_bf16(ring[i % RING], pb[(i - NQK) >> 2], o[(i - NQK) & 3], 0, 0, 0);
;           }
;           if (i + RING < NM) B_FRAG(ring[i % RING], i + RING);
;           if (i >= NQK + 2) {
;             const int g = i - NQK - 2;
;             f32x2 v;
;             if (g < 8) { v[0] = __builtin_amdgcn_exp2f(s0[2 * g]); v[1] = __builtin_amdgcn_exp2f(s0[2 * g + 1]); }
;             else       { v[0] = __builtin_amdgcn_exp2f(s1[2 * (g - 8)]); v[1] = __builtin_amdgcn_exp2f(s1[2 * (g - 8) + 1]); }
;             ps2 += v; w_[g] = cvtpk(v[0], v[1]);
;           }
;           __builtin_amdgcn_sched_barrier(0);
;         }
; #pragma unroll
.Lb_first:
	v_mov_b32_e32 v156, v92
	v_mov_b32_e32 v152, v88
	v_mov_b32_e32 v148, v84
	v_mov_b32_e32 v144, v80
	s_bitcmp1_b32 s42, 0
	s_cselect_b32 s99, 0x4400, 0
	v_add_u32_e32 v164, s99, v205
	ds_read_b128 v[252:255], v164
	ds_read_b128 v[178:181], v164 offset:32
	ds_read_b128 v[182:185], v164 offset:8736
	ds_read_b128 v[186:189], v164 offset:8768
	ds_read_b128 v[190:193], v164 offset:64
	ds_read_b128 v[194:197], v164 offset:96
	ds_read_b128 v[214:217], v164 offset:8800
	s_branch .Lb_body
	.p2align 3
.Lb_top:
	s_bitcmp1_b32 s42, 0
	s_cselect_b32 s99, 0x4400, 0
	v_add_u32_e32 v164, s99, v205
	ds_read_b128 v[252:255], v164
	ds_read_b128 v[178:181], v164 offset:32
	ds_read_b128 v[182:185], v164 offset:8736
	ds_read_b128 v[186:189], v164 offset:8768
	ds_read_b128 v[190:193], v164 offset:64
	ds_read_b128 v[194:197], v164 offset:96
	ds_read_b128 v[214:217], v164 offset:8800
	s_nop 7
	v_exp_f32_e32 v246, v80
	v_exp_f32_e32 v247, v81
	s_nop 0
	v_add_f32_e32 v250, 0, v246
	v_add_f32_e32 v251, 0, v247
	v_exp_f32_e32 v248, v82
	v_exp_f32_e32 v249, v83
	v_cvt_pk_bf16_f32 v144, v246, v247
	v_add_f32_e32 v250, v248, v250
	v_add_f32_e32 v251, v249, v251
	v_exp_f32_e32 v246, v84
	v_exp_f32_e32 v247, v85
	v_cvt_pk_bf16_f32 v145, v248, v249
	v_add_f32_e32 v250, v246, v250
	v_add_f32_e32 v251, v247, v251
	v_exp_f32_e32 v248, v86
	v_exp_f32_e32 v249, v87
	v_cvt_pk_bf16_f32 v146, v246, v247
	v_add_f32_e32 v250, v248, v250
	v_add_f32_e32 v251, v249, v251
	v_exp_f32_e32 v246, v88
	v_exp_f32_e32 v247, v89
	v_cvt_pk_bf16_f32 v147, v248, v249
	v_add_f32_e32 v250, v246, v250
	v_add_f32_e32 v251, v247, v251
	v_exp_f32_e32 v248, v90
	v_exp_f32_e32 v249, v91
	v_cvt_pk_bf16_f32 v148, v246, v247
	v_add_f32_e32 v250, v248, v250
	v_add_f32_e32 v251, v249, v251
	v_exp_f32_e32 v246, v92
	v_exp_f32_e32 v247, v93
	v_cvt_pk_bf16_f32 v149, v248, v249
	v_add_f32_e32 v250, v246, v250
	v_add_f32_e32 v251, v247, v251
	v_exp_f32_e32 v248, v94
	v_exp_f32_e32 v249, v95
	v_cvt_pk_bf16_f32 v150, v246, v247
	v_add_f32_e32 v250, v248, v250
	v_add_f32_e32 v251, v249, v251
	v_exp_f32_e32 v246, v64
	v_exp_f32_e32 v247, v65
	v_cvt_pk_bf16_f32 v151, v248, v249
	v_add_f32_e32 v250, v246, v250
	v_add_f32_e32 v251, v247, v251
	v_exp_f32_e32 v248, v66
	v_exp_f32_e32 v249, v67
	v_cvt_pk_bf16_f32 v152, v246, v247
	v_add_f32_e32 v250, v248, v250
	v_add_f32_e32 v251, v249, v251
	v_exp_f32_e32 v246, v68
	v_exp_f32_e32 v247, v69
	v_cvt_pk_bf16_f32 v153, v248, v249
	v_add_f32_e32 v250, v246, v250
	v_add_f32_e32 v251, v247, v251
	v_exp_f32_e32 v248, v70
	v_exp_f32_e32 v249, v71
	v_cvt_pk_bf16_f32 v154, v246, v247
	v_add_f32_e32 v250, v248, v250
	v_add_f32_e32 v251, v249, v251
	v_exp_f32_e32 v246, v72
	v_exp_f32_e32 v247, v73
	v_cvt_pk_bf16_f32 v155, v248, v249
	v_add_f32_e32 v250, v246, v250
	v_add_f32_e32 v251, v247, v251
	v_exp_f32_e32 v248, v74
	v_exp_f32_e32 v249, v75
	v_cvt_pk_bf16_f32 v156, v246, v247
	v_add_f32_e32 v250, v248, v250
	v_add_f32_e32 v251, v249, v251
	v_exp_f32_e32 v246, v76
	v_exp_f32_e32 v247, v77
	v_cvt_pk_bf16_f32 v157, v248, v249
	v_add_f32_e32 v250, v246, v250
	v_add_f32_e32 v251, v247, v251
	v_exp_f32_e32 v248, v78
	v_exp_f32_e32 v249, v79
	v_cvt_pk_bf16_f32 v158, v246, v247
	v_add_f32_e32 v250, v248, v250
	v_add_f32_e32 v251, v249, v251
	v_cvt_pk_bf16_f32 v159, v248, v249
	v_add_f32_e32 v250, v250, v251
	v_add_f32_e32 v176, v176, v250
.Lb_body:
	s_add_i32 s27, s42, 1
	s_bitcmp1_b32 s27, 0
	s_cselect_b64 s[20:21], -1, 0
	s_and_b64 s[22:23], s[20:21], exec
	s_cselect_b32 s26, 0x4400, 0
	s_bitcmp1_b32 s42, 0
	s_cselect_b64 s[22:23], -1, 0
	s_and_b64 s[44:45], s[22:23], exec
	s_cselect_b32 s43, 0x4800, 0
	s_waitcnt lgkmcnt(6)
	v_mfma_f32_32x32x16_bf16 v[80:95], v[252:255], v[100:103], 0
	ds_read_b128 v[68:71], v164 offset:8704
	ds_read_b128 v[220:223], v164 offset:128
	s_and_b64 s[20:21], s[20:21], exec
	s_cselect_b32 s20, 0x4800, 0
	v_add_u32_e32 v177, s20, v206
	ds_read_b128 v[224:227], v164 offset:8832
	s_waitcnt lgkmcnt(2)
	v_mfma_f32_32x32x16_bf16 v[64:79], v[68:71], v[100:103], 0
	v_mfma_f32_32x32x16_bf16 v[80:95], v[178:181], v[108:111], v[80:95]
	ds_read_b128 v[228:231], v164 offset:160
	ds_read_b128 v[178:181], v164 offset:8864
	s_waitcnt vmcnt(0)
	v_add_u32_e32 v238, s26, v203
	ds_write_b128 v238, v[128:131]
	v_mfma_f32_32x32x16_bf16 v[64:79], v[182:185], v[108:111], v[64:79]
	ds_write_b128 v238, v[132:135] offset:128
	v_mfma_f32_32x32x16_bf16 v[80:95], v[190:193], v[96:99], v[80:95]
	ds_read_b128 v[182:185], v164 offset:192
	ds_read_b128 v[190:193], v164 offset:8896
	v_add_u32_e32 v239, s43, v204
	ds_write_b128 v239, v[136:139] offset:34816
	v_mfma_f32_32x32x16_bf16 v[64:79], v[186:189], v[96:99], v[64:79]
	ds_write_b128 v239, v[140:143] offset:44032
	v_mfma_f32_32x32x16_bf16 v[80:95], v[194:197], v[104:107], v[80:95]
	ds_read_b128 v[186:189], v164 offset:224
	ds_read_b128 v[194:197], v164 offset:8928
	s_cmp_gt_u32 s27, 61
	s_cbranch_scc1 .Lmy_b_skipk
	s_cmp_eq_u32 s42, 60
	s_cselect_b64 vcc, -1, 0
	s_add_u32 s42, s6, s24
	v_cndmask_b32_e32 v242, v160, v201, vcc
	s_addc_u32 s43, s7, s25
	v_mov_b32_e32 v243, 0
	v_lshl_add_u64 v[240:241], s[42:43], 0, v[242:243]
	v_add_co_u32_e32 v240, vcc, 0x38b18000, v240
	s_nop 1
	v_addc_co_u32_e32 v241, vcc, 0, v241, vcc
	global_load_dwordx4 v[128:131], v[240:241], off
	global_load_dwordx4 v[132:135], v[240:241], off offset:128
; DI unsigned cvtpk(float lo, float hi) { f32x2 v = {lo, hi}; return __builtin_bit_cast(unsigned, __builtin_convertvector(v, bf16x2_t)); }
; template <int NHQ, int NHKV>
; DI void attn_phase_l1(const u16* __restrict__ Q, const u16* __restrict__ K, const u16* __restrict__ Vt, u16* __restrict__ O, const float* __restrict__ qg, char* smem, const int wv) {
;     ...
;         for (int i = 0; i < NM; ++i) {
;           if (i < NQK) {
;             if (i & 1) s1 = __builtin_amdgcn_mfma_f32_32x32x16_bf16(ring[i % RING], qf[i >> 1], s1, 0, 0, 0);
;             else       s0 = __builtin_amdgcn_mfma_f32_32x32x16_bf16(ring[i % RING], qf[i >> 1], s0, 0, 0, 0);
;           } else {
;             o[(i - NQK) & 3] = __builtin_amdgcn_mfma_f32_32x32x16_bf16(ring[i % RING], pb[(i - NQK) >> 2], o[(i - NQK) & 3], 0, 0, 0);
;           }
;           if (i + RING < NM) B_FRAG(ring[i % RING], i + RING);
;           if (i >= NQK + 2) {
;             const int g = i - NQK - 2;
;             f32x2 v;
;             if (g < 8) { v[0] = __builtin_amdgcn_exp2f(s0[2 * g]); v[1] = __builtin_amdgcn_exp2f(s0[2 * g + 1]); }
;             else       { v[0] = __builtin_amdgcn_exp2f(s1[2 * (g - 8)]); v[1] = __builtin_amdgcn_exp2f(s1[2 * (g - 8) + 1]); }
;             ps2 += v; w_[g] = cvtpk(v[0], v[1]);
;           }
;           __builtin_amdgcn_sched_barrier(0);
;         }
; #pragma unroll
;         for (int g = 14; g < 16; ++g) { f32x2 v; v[0] = __builtin_amdgcn_exp2f(s1[2 * (g - 8)]); v[1] = __builtin_amdgcn_exp2f(s1[2 * (g - 8) + 1]); ps2 += v; w_[g] = cvtpk(v[0], v[1]); }
;     ...
;         if (j + 1 == NT - 1) {
;           ps2 = f32x2{0.f, 0.f};
; #pragma unroll
;           for (int g = 0; g < 4; ++g) { ps2[0] += __builtin_amdgcn_exp2f(s0[2 * g]); ps2[1] += __builtin_amdgcn_exp2f(s0[2 * g + 1]); }
; #pragma unroll
;           for (int g = 4; g < 16; ++g) w_[g] = 0u;
;         }
;         if (j + 1 < NT) {
;           l += ps2[0] + ps2[1];
; #pragma unroll
;           for (int q = 0; q < 4; ++q) pb[q] = __builtin_bit_cast(bf16x8, u32x4{w_[4 * q], w_[4 * q + 1], w_[4 * q + 2], w_[4 * q + 3]});
;         }
;       }
;       asm volatile("s_waitcnt lgkmcnt(0)" ::: "memory"); __builtin_amdgcn_s_barrier(); asm volatile("" ::: "memory");
.Lmy_b_skipk:
	v_mfma_f32_32x32x16_bf16 v[64:79], v[214:217], v[104:107], v[64:79]
	v_lshl_add_u64 v[240:241], s[6:7], 0, v[174:175]
	v_add_co_u32_e32 v244, vcc, 0x29900000, v240
	s_nop 1
	v_addc_co_u32_e32 v245, vcc, 0, v241, vcc
	v_add_co_u32_e32 v240, vcc, 0x29982000, v240
	s_nop 1
	v_addc_co_u32_e32 v241, vcc, 0, v241, vcc
	global_load_dwordx4 v[136:139], v[244:245], off offset:256
	global_load_dwordx4 v[140:143], v[240:241], off offset:256
	s_waitcnt lgkmcnt(11)
	v_mfma_f32_32x32x16_bf16 v[80:95], v[220:223], v[116:119], v[80:95]
	ds_read_b128 v[214:217], v177 offset:34816
	ds_read_b128 v[220:223], v177 offset:39424
	s_waitcnt lgkmcnt(11)
	v_mfma_f32_32x32x16_bf16 v[64:79], v[224:227], v[116:119], v[64:79]
	v_mfma_f32_32x32x16_bf16 v[80:95], v[228:231], v[120:123], v[80:95]
	ds_read_b128 v[224:227], v177 offset:44032
	ds_read_b128 v[228:231], v177 offset:48640
	s_waitcnt lgkmcnt(9)
	v_mfma_f32_32x32x16_bf16 v[64:79], v[178:181], v[120:123], v[64:79]
	v_mfma_f32_32x32x16_bf16 v[80:95], v[182:185], v[112:115], v[80:95]
	ds_read_b128 v[178:181], v177 offset:34848
	ds_read_b128 v[182:185], v177 offset:39456
	s_waitcnt lgkmcnt(7)
	v_mfma_f32_32x32x16_bf16 v[64:79], v[190:193], v[112:115], v[64:79]
	v_mfma_f32_32x32x16_bf16 v[80:95], v[186:189], v[124:127], v[80:95]
	ds_read_b128 v[190:193], v177 offset:44064
	ds_read_b128 v[186:189], v177 offset:48672
	s_waitcnt lgkmcnt(7)
	v_mfma_f32_32x32x16_bf16 v[64:79], v[194:197], v[124:127], v[64:79]
	v_mfma_f32_32x32x16_bf16 v[48:63], v[214:217], v[144:147], v[48:63]
	ds_read_b128 v[194:197], v177 offset:34880
	s_waitcnt lgkmcnt(7)
	v_mfma_f32_32x32x16_bf16 v[32:47], v[220:223], v[144:147], v[32:47]
	ds_read_b128 v[214:217], v177 offset:39488
	s_waitcnt lgkmcnt(7)
	v_mfma_f32_32x32x16_bf16 v[16:31], v[224:227], v[144:147], v[16:31]
	ds_read_b128 v[220:223], v177 offset:44096
	s_waitcnt lgkmcnt(7)
	v_mfma_f32_32x32x16_bf16 v[0:15], v[228:231], v[144:147], v[0:15]
	ds_read_b128 v[224:227], v177 offset:48704
	s_waitcnt lgkmcnt(7)
	v_mfma_f32_32x32x16_bf16 v[48:63], v[178:181], v[148:151], v[48:63]
	ds_read_b128 v[228:231], v177 offset:34912
	s_waitcnt lgkmcnt(7)
	v_mfma_f32_32x32x16_bf16 v[32:47], v[182:185], v[148:151], v[32:47]
	ds_read_b128 v[178:181], v177 offset:39520
	s_waitcnt lgkmcnt(7)
	v_mfma_f32_32x32x16_bf16 v[16:31], v[190:193], v[148:151], v[16:31]
	ds_read_b128 v[182:185], v177 offset:44128
	s_waitcnt lgkmcnt(7)
	v_mfma_f32_32x32x16_bf16 v[0:15], v[186:189], v[148:151], v[0:15]
	ds_read_b128 v[190:193], v177 offset:48736
	s_waitcnt lgkmcnt(6)
	v_mfma_f32_32x32x16_bf16 v[48:63], v[194:197], v[152:155], v[48:63]
	v_mfma_f32_32x32x16_bf16 v[32:47], v[214:217], v[152:155], v[32:47]
	s_waitcnt lgkmcnt(4)
	v_mfma_f32_32x32x16_bf16 v[16:31], v[220:223], v[152:155], v[16:31]
	v_mfma_f32_32x32x16_bf16 v[0:15], v[224:227], v[152:155], v[0:15]
	s_waitcnt lgkmcnt(2)
	v_mfma_f32_32x32x16_bf16 v[48:63], v[228:231], v[156:159], v[48:63]
	v_mfma_f32_32x32x16_bf16 v[32:47], v[178:181], v[156:159], v[32:47]
	s_waitcnt lgkmcnt(0)
	v_mfma_f32_32x32x16_bf16 v[16:31], v[182:185], v[156:159], v[16:31]
	v_mfma_f32_32x32x16_bf16 v[0:15], v[190:193], v[156:159], v[0:15]
	s_waitcnt lgkmcnt(0)
	s_add_u32 s24, s24, 0x8000
	s_addc_u32 s25, s25, 0
	s_cmp_eq_u32 s27, 62
	v_lshl_add_u64 v[174:175], v[174:175], 0, s[16:17]
	s_barrier
	s_cbranch_scc1 .Lb_exit
	s_mov_b32 s42, s27
	s_branch .Lb_top
